# static s_setprio 1 for younger blocks (blockIdx>=256) at entry and after scan exit
# speedup vs baseline: 1.0118x; 1.0023x over previous
; __device__ __forceinline__ int ltid() { int t = threadIdx.x; asm volatile("" : "+v"(t)); return t; }
; __device__ __forceinline__ void phase0(const Params& p, unsigned char* smem) {
;   u16* hn = (u16*)p.out; u16* wtin = hn + (size_t)NTOK * DM;
;   u16* w3 = (u16*)(p.ws + OFF_W3);
;   const int tid = ltid(), lane = tid & 63, wave = tid >> 6;
;   constexpr int N_HN = NTOK / 4;
;   constexpr int NT_IN = 161;
;   constexpr int N_TR = 16 * NT_IN + 3 * 256;
;   constexpr int N_MISC = 16;
;   for (int it = blockIdx.x; it < N_HN + N_TR + N_MISC; it += gridDim.x) {
;     if (it < N_HN) {
;       int row = it * 4 + wave; int b = row / LTOK, pos = row - b * LTOK;
;       const float* src = pos < NMETA ? p.meta + pos * DM : p.x + ((size_t)b * SEQ + pos - NMETA) * DM;
;       float4 v[4]; float ss = 0.f;
; #pragma unroll
;       for (int i = 0; i < 4; ++i) { v[i] = ((const float4*)src)[lane + 64 * i]; ss += v[i].x * v[i].x + v[i].y * v[i].y + v[i].z * v[i].z + v[i].w * v[i].w; }
; __global__ void __launch_bounds__(256, 2) mega(Params p) {
;   extern __shared__ __attribute__((aligned(16))) unsigned char smem[];
;   cg::grid_group grid = cg::this_grid();
;   unsigned* bar = (unsigned*)(p.ws + OFF_BAR);
;   phase0(p, smem); grid.sync();
_Z4mega6Params:
	s_load_dwordx4 s[48:51], s[0:1], 0x88
	s_load_dword s3, s[0:1], 0x98
	s_add_u32 s16, s0, 0x98
	s_mov_b32 s89, s2
	s_addc_u32 s17, s1, 0
	v_and_b32_e32 v218, 0x3ff, v0
	s_movk_i32 s2, 0x3ff
	v_mov_b32_e32 v2, v218
	s_cmpk_lt_u32 s89, 0x100
	s_cbranch_scc1 .Lprio_a
	s_setprio 1
.Lprio_a:
	s_cmpk_gt_i32 s89, 0x1d27
	v_mbcnt_lo_u32_b32 v219, -1, 0
	s_cbranch_scc1 .LBB0_73
	s_waitcnt lgkmcnt(0)
	s_add_u32 s18, s48, 0x2010000
	s_addc_u32 s19, s49, 0
	s_add_u32 s33, s50, 0xe81d000
	v_lshlrev_b32_e32 v5, 1, v2
	s_addc_u32 s40, s51, 0
	v_and_b32_e32 v22, 62, v5
	v_ashrrev_i32_e32 v5, 5, v2
	v_ashrrev_i32_e32 v1, 6, v2
	v_ashrrev_i32_e32 v3, 31, v2
	s_add_u32 s22, s0, 24
	s_movk_i32 s10, 0x104
	v_mul_u32_u24_e32 v8, 0x104, v22
	v_lshlrev_b32_e32 v9, 2, v5
	s_addc_u32 s23, s1, 0
	v_mul_lo_u32 v24, v1, s10
	v_add3_u32 v44, 16, v8, v9
	v_lshl_add_u64 v[8:9], v[2:3], 2, s[50:51]
	s_load_dwordx8 s[52:59], s[0:1], 0x20
	s_mov_b64 s[10:11], 0xf223000
	s_add_u32 s24, s50, 0x3018000
	v_lshl_add_u64 v[8:9], v[8:9], 0, s[10:11]
	s_load_dwordx4 s[12:15], s[0:1], 0x0
	s_load_dwordx2 s[10:11], s[0:1], 0x10
	s_addc_u32 s25, s51, 0
	v_and_b32_e32 v4, 63, v2
	s_add_u32 s26, s50, 0x4054020
	v_mov_b32_e32 v7, 0
	v_lshlrev_b32_e32 v6, 2, v4
	s_addc_u32 s27, s51, 0
	v_add_u32_e32 v23, 16, v6
	s_waitcnt lgkmcnt(0)
	v_lshl_add_u64 v[10:11], s[52:53], 0, v[6:7]
	v_lshl_add_u64 v[12:13], s[54:55], 0, v[6:7]
	v_lshl_add_u64 v[14:15], s[56:57], 0, v[6:7]
	v_lshl_add_u64 v[16:17], s[58:59], 0, v[6:7]
	s_add_u32 s28, s50, 0xf223040
	v_lshlrev_b32_e32 v6, 4, v4
	v_lshl_add_u32 v3, s89, 8, v2
	s_addc_u32 s29, s51, 0
	v_lshl_add_u64 v[18:19], s[10:11], 0, v[6:7]
	global_load_dwordx4 v[100:103], v[18:19], off
	global_load_dwordx4 v[104:107], v[18:19], off offset:1024
	global_load_dwordx4 v[108:111], v[18:19], off offset:2048
	global_load_dwordx4 v[112:115], v[18:19], off offset:3072
	v_add_u32_e32 v45, 0xffe2e800, v3
	s_lshl_b32 s41, s3, 8
	v_lshlrev_b32_e32 v6, 3, v4
	s_mov_b32 s30, 0xffff0000
	v_cmp_gt_i32_e64 s[8:9], 16, v2
	v_cmp_eq_u32_e64 s[4:5], 1, v1
	s_mov_b32 s21, 0
	v_cmp_eq_u32_e64 s[6:7], 0, v4
	v_add_u32_e32 v32, 16, v1
	v_add_u32_e32 v33, 20, v1
	v_add_u32_e32 v34, 24, v1
	v_add_u32_e32 v35, 28, v1
	v_add_u32_e32 v36, 32, v1
	v_add_u32_e32 v37, 36, v1
	v_add_u32_e32 v38, 40, v1
	v_add_u32_e32 v39, 44, v1
	v_add_u32_e32 v40, 48, v1
	v_add_u32_e32 v41, 52, v1
	v_add_u32_e32 v42, 56, v1
	v_add_u32_e32 v43, 60, v1
	s_sub_i32 s42, 0, s41
	v_lshl_add_u64 v[20:21], s[48:49], 0, v[6:7]
	s_mov_b32 s43, 0x1d27ff
	v_sub_u32_e32 v46, 0x1d27ff, v3
	s_mov_b32 s44, 0xc000
	s_movk_i32 s45, 0xfff
	s_mov_b32 s46, 0x2aaaaaab
	s_movk_i32 s47, 0xa000
	s_mov_b32 s52, 0xafff
	s_movk_i32 s53, 0xffe8
	s_movk_i32 s54, 0x4080
	s_movk_i32 s55, 0x70
	v_lshlrev_b32_e32 v6, 1, v22
	s_mov_b32 s56, 0x7fc01ff1
	s_movk_i32 s57, 0xdff0
	s_mov_b32 s31, -1
	v_lshlrev_b32_e32 v22, 4, v4
	v_mov_b32_e32 v47, 0x358637bd
	s_mov_b32 s58, 0x800000
	v_mbcnt_hi_u32_b32 v48, -1, v219
	v_add_u32_e32 v49, v23, v24
	v_mov_b32_e32 v50, v45
	s_mov_b32 s59, 0
	s_mov_b32 s60, s89
	s_waitcnt vmcnt(0)
	s_branch .LBB0_4

; __device__ __forceinline__ void phase3(const Params& p, unsigned char* smem, unsigned* bar) {
;     ...
;     scan_chunked(p, smem, blockIdx.x, S, 0, NCH);
;   } else {
;     phase2<true>(p, smem, P2_SPLIT * 16, NCH * 16, blockIdx.x - 16, gridDim.x - 16);
;   }
;   int* cnt = (int*)(p.ws + OFF_CTL);
;   const float lam = ((const float*)(p.ws + OFF_CTL))[16];
;   const int myq = blockIdx.x & 7;
;   for (int qq = 0; qq < 8; ++qq) {
;     const int q = (myq + qq) & 7;
.LBB0_320:
	s_setprio 0
	s_cmpk_lt_u32 s89, 0x100
	s_cbranch_scc1 .Lprio_b
	s_setprio 1
